# Hyena-output transpose items dealt to the workgroups with the least mixer work (bid&7 in {0,7}) so they run in the mixer's load-imbalance slack
# speedup vs baseline: 1.0108x; 1.0047x over previous
.LBB0_1253:
	s_or_b64 exec, exec, s[6:7]
	s_mov_b64 s[6:7], s[66:67]
	v_mov_b32_e32 v0, v1
	s_waitcnt lgkmcnt(0)
	s_barrier
	s_nop 0
	v_mbcnt_lo_u32_b32 v0, -1, v0
	v_mbcnt_hi_u32_b32 v0, -1, v0
	v_add_u32_e32 v2, s86, v0
	s_nop 0
	v_readfirstlane_b32 s0, v2
	s_ashr_i32 s2, s0, 6
	s_cmpk_lg_i32 s68, 0x800
	s_cbranch_scc1 .Lytm_orig
	s_lshr_b32 s0, s55, 3
	s_and_b32 s1, s0, 7
	s_lshr_b32 s0, s0, 3
	s_lshl_b32 s0, s0, 4
	s_add_i32 s0, s0, s2
	s_cmp_eq_u32 s1, 0
	s_cbranch_scc1 .Lytm_it
	s_add_i32 s0, s0, 8
	s_cmp_lg_u32 s1, 7
	s_cbranch_scc1 .LBB0_1256
	s_branch .Lytm_it
.Lytm_orig:
	s_add_i32 s0, s2, s55
	s_cmpk_gt_i32 s0, 0x1ff
	s_cbranch_scc1 .LBB0_1256
.Lytm_it:
	s_load_dwordx2 s[6:7], s[6:7], 0x100
	v_and_b32_e32 v4, 7, v0
	v_bfe_u32 v12, v0, 3, 3
	v_lshlrev_b32_e32 v0, 4, v4
	s_lshl_b32 s1, s2, 14
	s_waitcnt lgkmcnt(0)
	v_lshl_add_u64 v[2:3], s[6:7], 0, v[0:1]
	s_and_b32 s3, s2, 3
	s_lshl_b32 s3, s3, 7
	s_add_u32 s3, s3, 0xe803800
	s_add_u32 s6, s6, s3
	s_addc_u32 s7, s7, 0
	v_readlane_b32 s3, v255, 21
	s_nop 3
	s_add_i32 s3, s3, 1
	s_lshl_b32 s3, s3, 6

.Lytf_go:
	s_mov_b64 s[6:7], 0xb800000
	v_lshl_add_u64 v[6:7], v[2:3], 0, s[6:7]
	s_mov_b64 s[6:7], 0xd800000
	s_add_i32 s1, s1, 0
	v_mul_u32_u24_e32 v4, 0x420, v4
	v_lshl_add_u64 v[8:9], v[2:3], 0, s[6:7]
	v_lshlrev_b32_e32 v2, 1, v12
	v_add_u32_e32 v0, s1, v0
	v_add3_u32 v13, s1, v4, v2
	s_lshl_b32 s1, s2, 4
	v_readlane_b32 s3, v254, 48
	v_mul_u32_u24_e32 v2, 0x84, v12
	s_lshl_b32 s1, s0, 4
	s_lshl_b32 s2, s2, 6
	v_readlane_b32 s3, v254, 7
	v_or_b32_e32 v14, 8, v12
	v_or_b32_e32 v15, 16, v12
	v_or_b32_e32 v16, 24, v12
	v_or_b32_e32 v17, 32, v12
	v_or_b32_e32 v18, 40, v12
	v_or_b32_e32 v19, 48, v12
	v_or_b32_e32 v20, 56, v12
	s_lshl_b32 s2, s0, 6
	v_add_u32_e32 v21, v0, v2
